# final RMSNorm row loop software-pipelined: next row's x loads issued while the current row is reduced (separate raw registers, persistent address); on top of v53
# baseline (speedup 1.0000x reference)
; DI float h_lo(unsigned u) { return (float)__builtin_bit_cast(h2_t, u)[0]; }
; DI float h_hi(unsigned u) { return (float)__builtin_bit_cast(h2_t, u)[1]; }
; DI int tid_opaque() { int t = threadIdx.x; asm volatile("" : "+v"(t)); return t; }
; #define G_XF (outp())
; __global__ void __launch_bounds__(512, 2) mega(Params p) {
;     ...
;   {
;     const int t2 = tid_opaque();
;     const int w = t2 >> 6, l = t2 & 63;
;     const float4* gf = (const float4*)inp(23);
;     for (int row = bid * 8 + w; row < NTOK; row += nb * 8) {
;       const uint2* xp = (const uint2*)(G_XB + (size_t)row * DM);
;       float4* op = (float4*)(G_XF + (size_t)row * DM);
;       float4 v[4];
;       float s2 = 0.f;
; #pragma unroll
;       for (int i = 0; i < 4; ++i) {
;         const uint2 u = xp[l + 64 * i];
;         v[i].x = h_lo(u.x); v[i].y = h_hi(u.x);
;         v[i].z = h_lo(u.y); v[i].w = h_hi(u.y);
;         s2 += v[i].x * v[i].x + v[i].y * v[i].y + v[i].z * v[i].z + v[i].w * v[i].w;
;       }
; #pragma unroll
;       for (int o = 32; o; o >>= 1) s2 += __shfl_xor(s2, o);
;       const float rr = rsqrtf(s2 * (1.f / 1024.f) + EPS);
; #pragma unroll
;       for (int i = 0; i < 4; ++i) {
;         const float4 g = gf[l + 64 * i];
;         float4 o4 = {v[i].x * rr * g.x, v[i].y * rr * g.y, v[i].z * rr * g.z, v[i].w * rr * g.w};
;         op[l + 64 * i] = o4;
;       }
;     }
;   }
.LBB0_1413:
	v_readlane_b32 s1, v252, 5
	v_ashrrev_i32_e32 v0, 6, v224
	s_mov_b32 s0, 23
	v_add_u32_e32 v0, s1, v0
	s_movk_i32 s1, 0x4000
	v_cmp_gt_i32_e32 vcc, s1, v0
	s_and_saveexec_b64 s[2:3], vcc
	s_cbranch_execz .LBB0_1416
	s_ashr_i32 s1, s0, 31
	s_lshl_b64 s[0:1], s[0:1], 3
	s_add_u32 s0, s70, s0
	s_addc_u32 s1, s71, s1
	s_load_dwordx2 s[2:3], s[0:1], 0x0
	v_readlane_b32 s0, v252, 1
	v_and_b32_e32 v6, 63, v224
	v_readlane_b32 s1, v252, 2
	v_ashrrev_i32_e32 v1, 31, v0
	v_lshlrev_b32_e32 v8, 4, v6
	s_lshl_b32 s0, s0, 3
	v_lshlrev_b64 v[4:5], 11, v[0:1]
	v_lshlrev_b32_e32 v6, 3, v6
	s_movk_i32 s1, 0x604
	v_mov_b32_e32 v9, 0
	v_or3_b32 v4, v4, v6, s1
	s_ashr_i32 s1, s0, 31
	v_lshlrev_b64 v[6:7], 12, v[0:1]
	s_movk_i32 s4, 0xc08
	v_and_b32_e32 v1, 64, v225
	s_waitcnt lgkmcnt(0)
	v_lshl_add_u64 v[2:3], s[2:3], 0, v[8:9]
	global_load_dwordx4 v[60:63], v[2:3], off
	global_load_dwordx4 v[64:67], v[2:3], off offset:1024
	global_load_dwordx4 v[68:71], v[2:3], off offset:2048
	global_load_dwordx4 v[72:75], v[2:3], off offset:3072
	s_lshl_b64 s[2:3], s[0:1], 11
	v_or3_b32 v6, v6, v8, s4
	s_lshl_b64 s[4:5], s[0:1], 12
	s_mov_b64 s[6:7], 0
	v_add_u32_e32 v1, 64, v1
	v_xor_b32_e32 v8, 32, v225
	v_xor_b32_e32 v9, 16, v225
	v_xor_b32_e32 v10, 8, v225
	v_xor_b32_e32 v11, 4, v225
	v_xor_b32_e32 v12, 2, v225
	v_xor_b32_e32 v13, 1, v225
	v_mov_b32_e32 v14, 0x358637bd
	s_mov_b32 s1, 0x800000
	s_movk_i32 s8, 0x3fff
	v_readlane_b32 s10, v255, 60
	v_readlane_b32 s11, v255, 61
	s_nop 4
	v_lshl_add_u64 v[96:97], s[10:11], 0, v[4:5]
	global_load_dwordx2 v[88:89], v[96:97], off offset:-1540
	global_load_dwordx2 v[90:91], v[96:97], off offset:-1028
	global_load_dwordx2 v[92:93], v[96:97], off offset:-516
	global_load_dwordx2 v[94:95], v[96:97], off offset:-4
	v_lshl_add_u64 v[96:97], v[96:97], 0, s[2:3]
	s_waitcnt vmcnt(0)
.LBB0_1415:
	s_mov_b32 s10, 25
	s_ashr_i32 s11, s10, 31
	s_lshl_b64 s[10:11], s[10:11], 3
	s_add_u32 s10, s70, s10
	s_addc_u32 s11, s71, s11
	v_readlane_b32 s10, v255, 60
	v_readlane_b32 s11, v255, 61
	s_nop 4
	s_mov_b32 s12, 24
	v_cmp_lt_i32_e32 vcc, v8, v1
	s_ashr_i32 s13, s12, 31
	s_waitcnt lgkmcnt(0)
	v_cndmask_b32_e32 v15, v225, v8, vcc
	v_cmp_lt_i32_e32 vcc, v9, v1
	v_lshlrev_b32_e32 v15, 2, v15
	s_lshl_b64 s[10:11], s[12:13], 3
	v_cndmask_b32_e32 v16, v225, v9, vcc
	v_cmp_lt_i32_e32 vcc, v10, v1
	v_lshlrev_b32_e32 v54, 2, v16
	s_add_u32 s10, s70, s10
	v_cndmask_b32_e32 v17, v225, v10, vcc
	v_cmp_lt_i32_e32 vcc, v11, v1
	v_lshlrev_b32_e32 v55, 2, v17
	s_addc_u32 s11, s71, s11
	v_cndmask_b32_e32 v18, v225, v11, vcc
	v_cmp_lt_i32_e32 vcc, v12, v1
	v_lshlrev_b32_e32 v56, 2, v18
	s_load_dwordx2 s[10:11], s[10:11], 0x0
	v_cndmask_b32_e32 v19, v225, v12, vcc
	v_lshlrev_b32_e32 v57, 2, v19
	v_cmp_lt_i32_e32 vcc, v13, v1
	v_add_u32_e32 v0, s0, v0
	v_lshl_add_u64 v[4:5], v[4:5], 0, s[2:3]
	v_cndmask_b32_e32 v28, v225, v13, vcc
	v_lshlrev_b32_e32 v58, 2, v28
	s_waitcnt lgkmcnt(0)
	v_lshl_add_u64 v[28:29], s[10:11], 0, v[6:7]
	v_lshl_add_u64 v[6:7], v[6:7], 0, s[4:5]
	s_waitcnt vmcnt(4)
	v_cvt_f32_f16_sdwa v31, v88 dst_sel:DWORD dst_unused:UNUSED_PAD src0_sel:WORD_1
	v_cvt_f32_f16_sdwa v33, v90 dst_sel:DWORD dst_unused:UNUSED_PAD src0_sel:WORD_1
	v_cvt_f32_f16_e32 v30, v88
	v_cvt_f32_f16_e32 v32, v90
	v_cvt_f32_f16_sdwa v35, v92 dst_sel:DWORD dst_unused:UNUSED_PAD src0_sel:WORD_1
	v_cvt_f32_f16_sdwa v37, v94 dst_sel:DWORD dst_unused:UNUSED_PAD src0_sel:WORD_1
	v_cvt_f32_f16_e32 v20, v89
	v_cvt_f32_f16_e32 v22, v91
	v_cvt_f32_f16_e32 v34, v92
	v_cvt_f32_f16_e32 v36, v94
	v_cvt_f32_f16_sdwa v21, v89 dst_sel:DWORD dst_unused:UNUSED_PAD src0_sel:WORD_1
	v_cvt_f32_f16_sdwa v23, v91 dst_sel:DWORD dst_unused:UNUSED_PAD src0_sel:WORD_1
	v_cvt_f32_f16_e32 v24, v93
	v_cvt_f32_f16_e32 v26, v95
	v_cvt_f32_f16_sdwa v25, v93 dst_sel:DWORD dst_unused:UNUSED_PAD src0_sel:WORD_1
	v_cvt_f32_f16_sdwa v27, v95 dst_sel:DWORD dst_unused:UNUSED_PAD src0_sel:WORD_1
	global_load_dwordx2 v[88:89], v[96:97], off offset:-1540
	global_load_dwordx2 v[90:91], v[96:97], off offset:-1028
	global_load_dwordx2 v[92:93], v[96:97], off offset:-516
	global_load_dwordx2 v[94:95], v[96:97], off offset:-4
	v_lshl_add_u64 v[96:97], v[96:97], 0, s[2:3]
	v_mov_b32_e32 v40, v31
	v_mov_b32_e32 v41, v33
	v_mov_b32_e32 v38, v30
	v_mov_b32_e32 v39, v32
	v_mov_b32_e32 v48, v35
	v_mov_b32_e32 v49, v37
	v_pk_mul_f32 v[40:41], v[40:41], v[40:41]
	v_mov_b32_e32 v42, v20
	v_mov_b32_e32 v43, v22
	v_mov_b32_e32 v46, v34
	v_mov_b32_e32 v47, v36
	v_pk_mul_f32 v[48:49], v[48:49], v[48:49]
	v_pk_fma_f32 v[38:39], v[38:39], v[38:39], v[40:41]
	v_mov_b32_e32 v44, v21
	v_mov_b32_e32 v45, v23
	v_mov_b32_e32 v50, v24
	v_mov_b32_e32 v51, v26
	v_pk_fma_f32 v[40:41], v[46:47], v[46:47], v[48:49]
	v_pk_fma_f32 v[38:39], v[42:43], v[42:43], v[38:39]
	v_mov_b32_e32 v52, v25
	v_mov_b32_e32 v53, v27
	v_pk_fma_f32 v[40:41], v[50:51], v[50:51], v[40:41]
	v_pk_fma_f32 v[38:39], v[44:45], v[44:45], v[38:39]
	v_pk_fma_f32 v[40:41], v[52:53], v[52:53], v[40:41]
	v_add_f32_e32 v38, v38, v39
	v_add_f32_e32 v38, v38, v40
	v_add_f32_e32 v38, v38, v41
	ds_bpermute_b32 v15, v15, v38
	s_waitcnt lgkmcnt(0)
	v_add_f32_e32 v15, v38, v15
	ds_bpermute_b32 v38, v54, v15
	s_waitcnt lgkmcnt(0)
	v_add_f32_e32 v15, v15, v38
	ds_bpermute_b32 v38, v55, v15
	s_waitcnt lgkmcnt(0)
	v_add_f32_e32 v15, v15, v38
	ds_bpermute_b32 v38, v56, v15
	s_waitcnt lgkmcnt(0)
	v_add_f32_e32 v15, v15, v38
	ds_bpermute_b32 v38, v57, v15
	s_waitcnt lgkmcnt(0)
	v_add_f32_e32 v15, v15, v38
	ds_bpermute_b32 v38, v58, v15
	s_waitcnt lgkmcnt(0)
	v_add_f32_e32 v15, v15, v38
	v_fmamk_f32 v15, v15, 0x3a800000, v14
	v_mul_f32_e32 v38, 0x4b800000, v15
	v_cmp_gt_f32_e32 vcc, s1, v15
	s_nop 1
	v_cndmask_b32_e32 v15, v15, v38, vcc
	v_rsq_f32_e32 v15, v15
	s_nop 0
	v_mul_f32_e32 v38, 0x45800000, v15
	v_cndmask_b32_e32 v38, v15, v38, vcc
	v_pk_mul_f32 v[30:31], v[38:39], v[30:31] op_sel_hi:[0,1]
	v_pk_mul_f32 v[20:21], v[38:39], v[20:21] op_sel_hi:[0,1]
	v_pk_mul_f32 v[16:17], v[60:61], v[30:31]
	v_pk_mul_f32 v[18:19], v[62:63], v[20:21]
	global_store_dwordx4 v[28:29], v[16:19], off offset:-3080
	v_pk_mul_f32 v[20:21], v[38:39], v[32:33] op_sel_hi:[0,1]
	v_pk_mul_f32 v[22:23], v[38:39], v[22:23] op_sel_hi:[0,1]
	v_cmp_lt_i32_e32 vcc, s8, v0
	s_or_b64 s[6:7], vcc, s[6:7]
	v_pk_mul_f32 v[76:77], v[64:65], v[20:21]
	v_pk_mul_f32 v[78:79], v[66:67], v[22:23]
	global_store_dwordx4 v[28:29], v[76:79], off offset:-2056
	v_pk_mul_f32 v[20:21], v[38:39], v[34:35] op_sel_hi:[0,1]
	v_pk_mul_f32 v[22:23], v[38:39], v[24:25] op_sel_hi:[0,1]
	v_pk_mul_f32 v[80:81], v[68:69], v[20:21]
	v_pk_mul_f32 v[82:83], v[70:71], v[22:23]
	global_store_dwordx4 v[28:29], v[80:83], off offset:-1032
	v_pk_mul_f32 v[20:21], v[38:39], v[36:37] op_sel_hi:[0,1]
	v_pk_mul_f32 v[22:23], v[38:39], v[26:27] op_sel_hi:[0,1]
	v_pk_mul_f32 v[84:85], v[72:73], v[20:21]
	v_pk_mul_f32 v[86:87], v[74:75], v[22:23]
	global_store_dwordx4 v[28:29], v[84:87], off offset:-8
	s_andn2_b64 exec, exec, s[6:7]
	s_cbranch_execnz .LBB0_1415
